# GQA: next unit's K tiles 0-2 LDS-DMA prefetched into the dead K ring during the last key tile (on top of Q prefetch)
# baseline (speedup 1.0000x reference)
.LBB0_291:
	s_ashr_i32 s16, s19, 7
	s_ashr_i32 s17, s16, 31
	s_lshl_b32 s24, s19, 8
	s_lshl_b64 s[40:41], s[16:17], 12
	s_and_b32 s24, s24, 0xf00
	s_bfe_u32 s36, s19, 0x10006
	s_or_b32 s40, s40, s24
	s_lshl_b32 s60, s36, 7
	s_lshl_b64 s[24:25], s[40:41], 12
	s_add_u32 s24, s50, s24
	s_addc_u32 s25, s51, s25
	s_lshl_b32 s37, s19, 2
	s_lshl_b32 s36, s36, 8
	s_and_b32 s37, s37, 0xc0
	s_or_b32 s47, s36, s37
	s_lshl_b32 s36, s47, 1
	s_add_u32 s48, s24, s36
	s_addc_u32 s49, s25, 0
	s_lshl_b64 s[16:17], s[16:17], 24
	s_add_u32 s24, s50, s16
	s_addc_u32 s25, s51, s17
	v_mov_b32_e32 v72, v192
	s_add_u32 s42, s24, s60
	s_addc_u32 s43, s25, 0
	v_readfirstlane_b32 s55, v72
	s_ashr_i32 s46, s55, 6
	s_lshl_b32 s36, s46, 5
	s_ashr_i32 s37, s36, 31
	s_lshl_b64 s[24:25], s[36:37], 12
	s_add_u32 s56, s48, s24
	v_and_b32_e32 v160, 63, v72
	s_addc_u32 s57, s49, s25
	s_mov_b64 s[76:77], s[56:57]
	s_lshl_b32 s24, s46, 3
	v_lshlrev_b32_e32 v188, 12, v160
	s_ashr_i32 s25, s24, 31
	v_lshl_add_u64 v[0:1], s[42:43], 0, v[188:189]
	s_lshl_b64 s[24:25], s[24:25], 1
	v_lshl_add_u64 v[40:41], v[0:1], 0, s[24:25]
	v_mov_b64_e32 v[194:195], v[40:41]
	s_mov_b64 s[48:49], 0xa00
	v_lshl_add_u64 v[154:155], v[40:41], 0, s[48:49]
	s_lshl_b32 s48, s46, 4
	v_bfe_u32 v73, v72, 2, 4
	v_and_or_b32 v0, s48, 48, v73
	v_lshlrev_b32_e32 v0, 12, v0
	v_mov_b32_e32 v1, v189
	v_lshl_add_u64 v[0:1], s[42:43], 0, v[0:1]
	s_ashr_i32 s42, s55, 3
	s_andn2_b32 s42, s42, 31
	s_ashr_i32 s43, s42, 31
	v_lshlrev_b32_e32 v161, 3, v72
	s_lshl_b64 s[42:43], s[42:43], 1
	v_and_b32_e32 v166, 24, v161
	v_lshl_add_u64 v[0:1], v[0:1], 0, s[42:43]
	v_lshlrev_b32_e32 v2, 1, v166
	v_mov_b32_e32 v3, v189
	s_lshl_b32 s54, s46, 10
	v_lshl_add_u64 v[64:65], v[0:1], 0, v[2:3]
	s_mov_b64 s[48:49], 0xb00
	s_cmp_lg_u32 0, -1
	v_lshl_add_u64 v[152:153], v[64:65], 0, s[48:49]
	s_cselect_b32 s48, 0, 0
	s_add_i32 s49, s54, s48
	s_cmp_lg_u32 s78, 0
	s_cbranch_scc1 .Lgqa_k0_have
	s_mov_b32 s58, m0
	s_mov_b32 m0, s49
	s_nop 0
	global_load_lds_dwordx4 v[154:155], off
	s_mov_b32 m0, s58
.Lgqa_k0_have:
	s_add_i32 s48, s49, 0x6000
	s_mov_b32 s58, m0
	s_mov_b32 m0, s48
	s_nop 0
	global_load_lds_dwordx4 v[152:153], off
	s_mov_b32 m0, s58
	s_mov_b64 s[58:59], 0x40a00
	v_and_b32_e32 v162, 31, v72
	v_lshl_add_u64 v[0:1], v[40:41], 0, s[58:59]
	v_bfe_u32 v163, v72, 5, 1
	s_add_i32 s58, s49, 0x2000
	s_cmp_lg_u32 s78, 0
	s_cbranch_scc1 .Lgqa_k1_have
	s_mov_b32 s59, m0
	s_mov_b32 m0, s58
	s_nop 0
	global_load_lds_dwordx4 v[0:1], off
	s_mov_b32 m0, s59
.Lgqa_k1_have:
	v_lshlrev_b32_e32 v0, 12, v162
	v_lshl_or_b32 v0, v163, 4, v0
	s_cmp_lg_u32 s78, 0
	s_cbranch_scc1 .Lgqa_q_have
	global_load_dwordx4 v[140:143], v0, s[56:57] offset:1536
	global_load_dwordx4 v[132:135], v0, s[56:57] offset:1568
	global_load_dwordx4 v[124:127], v0, s[56:57] offset:1600
	global_load_dwordx4 v[116:119], v0, s[56:57] offset:1632
.Lgqa_q_have:
	v_lshlrev_b32_e32 v0, 10, v163
	v_lshlrev_b32_e32 v1, 4, v162
	s_mov_b64 s[56:57], 0x80a00
	v_add3_u32 v165, 0, v0, v1
	v_lshl_add_u64 v[0:1], v[40:41], 0, s[56:57]
	s_add_i32 s56, s49, 0x4000
	s_cmp_lg_u32 s78, 0
	s_cbranch_scc1 .Lgqa_k2_have
	s_mov_b32 s57, m0
	s_mov_b32 m0, s56
	s_nop 0
	global_load_lds_dwordx4 v[0:1], off
	s_mov_b32 m0, s57
.Lgqa_k2_have:
	s_waitcnt vmcnt(3) lgkmcnt(0)
	s_barrier
	s_cmp_eq_u32 s78, 0
	s_cbranch_scc1 .Lgqa_nomov
	v_mov_b32_e32 v140, v196
	v_mov_b32_e32 v141, v197
	v_mov_b32_e32 v142, v198
	v_mov_b32_e32 v143, v199
	v_mov_b32_e32 v132, v200
	v_mov_b32_e32 v133, v201
	v_mov_b32_e32 v134, v202
	v_mov_b32_e32 v135, v203
	v_mov_b32_e32 v124, v204
	v_mov_b32_e32 v125, v205
	v_mov_b32_e32 v126, v206
	v_mov_b32_e32 v127, v207
	v_mov_b32_e32 v116, v208
	v_mov_b32_e32 v117, v209
	v_mov_b32_e32 v118, v210
	v_mov_b32_e32 v119, v211

.LBB0_292:
	v_add_u32_e32 v170, s59, v164
	ds_read_b64_tr_b16 v[172:173], v170 offset:24576
	ds_read_b64_tr_b16 v[174:175], v170 offset:25088
	v_add_f32_e32 v72, v48, v49
	v_add_f32_e32 v72, v50, v72
	v_add_f32_e32 v72, v51, v72
	v_add_f32_e32 v72, v52, v72
	v_add_f32_e32 v72, v53, v72
	v_cvt_pk_bf16_f32 v136, v48, v49
	v_cvt_pk_bf16_f32 v137, v50, v51
	s_waitcnt lgkmcnt(9)
	v_mfma_f32_32x32x16_bf16 v[80:95], v[68:71], v[140:143], 0
	ds_read_b64_tr_b16 v[48:49], v170 offset:28672
	ds_read_b64_tr_b16 v[50:51], v170 offset:29184
	v_add_f32_e32 v68, v54, v72
	v_add_f32_e32 v68, v55, v68
	v_add_f32_e32 v68, v56, v68
	v_add_f32_e32 v112, v57, v68
	s_waitcnt lgkmcnt(10)
	v_mfma_f32_32x32x16_bf16 v[64:79], v[64:67], v[140:143], 0
	v_cvt_pk_bf16_f32 v138, v52, v53
	v_cvt_pk_bf16_f32 v139, v54, v55
	ds_read_b64_tr_b16 v[52:53], v170 offset:25600
	ds_read_b64_tr_b16 v[54:55], v170 offset:26112
	v_add_f32_e32 v112, v58, v112
	v_add_f32_e32 v112, v59, v112
	v_add_f32_e32 v112, v60, v112
	v_add_f32_e32 v112, v61, v112
	v_cvt_pk_bf16_f32 v128, v56, v57
	v_cvt_pk_bf16_f32 v129, v58, v59
	s_waitcnt lgkmcnt(11)
	v_mfma_f32_32x32x16_bf16 v[80:95], v[148:151], v[132:135], v[80:95]
	ds_read_b64_tr_b16 v[56:57], v170 offset:29696
	ds_read_b64_tr_b16 v[58:59], v170 offset:30208
	s_waitcnt lgkmcnt(12)
	v_mfma_f32_32x32x16_bf16 v[64:79], v[144:147], v[132:135], v[64:79]
	v_add_f32_e32 v112, v62, v112
	v_add_f32_e32 v112, v63, v112
	v_add_f32_e32 v112, v32, v112
	v_add_f32_e32 v112, v33, v112
	v_cvt_pk_bf16_f32 v130, v60, v61
	v_cvt_pk_bf16_f32 v131, v62, v63
	ds_read_b64_tr_b16 v[60:61], v170 offset:26624
	ds_read_b64_tr_b16 v[62:63], v170 offset:27136
	s_waitcnt lgkmcnt(13)
	v_mfma_f32_32x32x16_bf16 v[80:95], v[108:111], v[124:127], v[80:95]
	v_add_f32_e32 v108, v34, v112
	v_add_f32_e32 v108, v35, v108
	v_add_f32_e32 v108, v36, v108
	v_add_f32_e32 v108, v37, v108
	v_cvt_pk_bf16_f32 v120, v32, v33
	v_cvt_pk_bf16_f32 v121, v34, v35
	ds_read_b64_tr_b16 v[32:33], v170 offset:30720
	ds_read_b64_tr_b16 v[34:35], v170 offset:31232
	s_waitcnt lgkmcnt(14)
	v_mfma_f32_32x32x16_bf16 v[64:79], v[104:107], v[124:127], v[64:79]
	v_add_f32_e32 v104, v38, v108
	v_add_f32_e32 v104, v39, v104
	v_add_f32_e32 v104, v40, v104
	v_add_f32_e32 v104, v41, v104
	v_cvt_pk_bf16_f32 v122, v36, v37
	v_cvt_pk_bf16_f32 v123, v38, v39
	ds_read_b64_tr_b16 v[36:37], v170 offset:27648
	ds_read_b64_tr_b16 v[38:39], v170 offset:28160
	s_waitcnt lgkmcnt(14)
	v_mfma_f32_32x32x16_bf16 v[80:95], v[100:103], v[116:119], v[80:95]
	v_add_f32_e32 v100, v42, v104
	v_add_f32_e32 v100, v43, v100
	v_add_f32_e32 v100, v44, v100
	v_add_f32_e32 v100, v45, v100
	v_cvt_pk_bf16_f32 v112, v40, v41
	v_cvt_pk_bf16_f32 v113, v42, v43
	ds_read_b64_tr_b16 v[40:41], v170 offset:31744
	ds_read_b64_tr_b16 v[42:43], v170 offset:32256
	v_mfma_f32_32x32x16_bf16 v[64:79], v[96:99], v[116:119], v[64:79]
	v_add_f32_e32 v96, v46, v100
	v_add_f32_e32 v96, v47, v96
	v_add_f32_e32 v170, 0, v96
	v_cvt_pk_bf16_f32 v114, v44, v45
	v_cvt_pk_bf16_f32 v115, v46, v47
	v_lshl_add_u64 v[44:45], v[158:159], 0, s[20:21]
	s_add_i32 s16, s58, s49
	s_mov_b32 s17, m0
	s_mov_b32 m0, s16
	s_nop 0
	global_load_lds_dwordx4 v[44:45], off
	s_mov_b32 m0, s17
	v_lshl_add_u64 v[44:45], v[156:157], 0, s[26:27]
	s_add_i32 s16, s57, s48
	s_mov_b32 s17, m0
	s_mov_b32 m0, s16
	s_nop 0
	global_load_lds_dwordx4 v[44:45], off
	s_mov_b32 m0, s17
	s_waitcnt lgkmcnt(14)
	v_mfma_f32_32x32x16_bf16 v[0:15], v[136:139], v[172:175], v[0:15]
	v_exp_f32_e32 v80, v80
	v_exp_f32_e32 v81, v81
	v_exp_f32_e32 v82, v82
	v_exp_f32_e32 v83, v83
	s_waitcnt lgkmcnt(12)
	v_mfma_f32_32x32x16_bf16 v[16:31], v[136:139], v[48:51], v[16:31]
	v_exp_f32_e32 v84, v84
	v_exp_f32_e32 v85, v85
	v_exp_f32_e32 v86, v86
	v_exp_f32_e32 v87, v87
	v_add_u32_e32 v48, s57, v165
	ds_read_b128 v[44:47], v48
	ds_read_b128 v[100:103], v48 offset:512
	s_waitcnt lgkmcnt(12)
	v_mfma_f32_32x32x16_bf16 v[0:15], v[128:131], v[52:55], v[0:15]
	v_exp_f32_e32 v88, v88
	v_exp_f32_e32 v89, v89
	v_exp_f32_e32 v90, v90
	v_exp_f32_e32 v91, v91
	ds_read_b128 v[104:107], v48 offset:2048
	ds_read_b128 v[108:111], v48 offset:2560
	s_waitcnt lgkmcnt(12)
	v_mfma_f32_32x32x16_bf16 v[16:31], v[128:131], v[56:59], v[16:31]
	v_exp_f32_e32 v92, v92
	v_exp_f32_e32 v93, v93
	v_exp_f32_e32 v94, v94
	v_exp_f32_e32 v95, v95
	ds_read_b128 v[144:147], v48 offset:4096
	ds_read_b128 v[148:151], v48 offset:4608
	s_waitcnt lgkmcnt(12)
	v_mfma_f32_32x32x16_bf16 v[0:15], v[120:123], v[60:63], v[0:15]
	v_exp_f32_e32 v64, v64
	v_exp_f32_e32 v65, v65
	v_exp_f32_e32 v66, v66
	v_exp_f32_e32 v67, v67
	ds_read_b128 v[172:175], v48 offset:6144
	ds_read_b128 v[96:99], v48 offset:6656
	s_waitcnt lgkmcnt(12)
	v_mfma_f32_32x32x16_bf16 v[16:31], v[120:123], v[32:35], v[16:31]
	v_exp_f32_e32 v68, v68
	v_exp_f32_e32 v69, v69
	v_exp_f32_e32 v70, v70
	v_exp_f32_e32 v71, v71
	s_waitcnt lgkmcnt(10)
	v_mfma_f32_32x32x16_bf16 v[0:15], v[112:115], v[36:39], v[0:15]
	v_exp_f32_e32 v72, v72
	v_exp_f32_e32 v73, v73
	v_exp_f32_e32 v74, v74
	v_exp_f32_e32 v75, v75
	s_waitcnt lgkmcnt(8)
	v_mfma_f32_32x32x16_bf16 v[16:31], v[112:115], v[40:43], v[16:31]
	v_exp_f32_e32 v76, v76
	v_exp_f32_e32 v77, v77
	v_exp_f32_e32 v78, v78
	v_exp_f32_e32 v79, v79
	s_waitcnt vmcnt(2) lgkmcnt(0)
	s_barrier
	s_add_i32 s16, s57, 0x2000
	s_cmpk_lg_i32 s57, 0x4000
	s_cselect_b32 s16, s16, 0
	v_add_u32_e32 v171, s58, v164
	ds_read_b64_tr_b16 v[176:177], v171 offset:24576
	ds_read_b64_tr_b16 v[178:179], v171 offset:25088
	s_waitcnt lgkmcnt(9)
	v_mfma_f32_32x32x16_bf16 v[48:63], v[44:47], v[140:143], 0
	v_add_f32_e32 v32, v80, v81
	v_add_f32_e32 v32, v82, v32
	v_add_f32_e32 v32, v83, v32
	v_add_f32_e32 v32, v84, v32
	v_add_f32_e32 v32, v85, v32
	v_cvt_pk_bf16_f32 v136, v80, v81
	v_cvt_pk_bf16_f32 v137, v82, v83
	ds_read_b64_tr_b16 v[80:81], v171 offset:28672
	ds_read_b64_tr_b16 v[82:83], v171 offset:29184
	v_add_f32_e32 v32, v86, v32
	v_add_f32_e32 v32, v87, v32
	v_add_f32_e32 v32, v88, v32
	v_add_f32_e32 v112, v89, v32
	s_waitcnt lgkmcnt(10)
	v_mfma_f32_32x32x16_bf16 v[32:47], v[100:103], v[140:143], 0
	v_cvt_pk_bf16_f32 v138, v84, v85
	v_cvt_pk_bf16_f32 v139, v86, v87
	ds_read_b64_tr_b16 v[84:85], v171 offset:25600
	ds_read_b64_tr_b16 v[86:87], v171 offset:26112
	s_waitcnt lgkmcnt(11)
	v_mfma_f32_32x32x16_bf16 v[48:63], v[104:107], v[132:135], v[48:63]
	v_add_f32_e32 v100, v90, v112
	v_add_f32_e32 v100, v91, v100
	v_add_f32_e32 v100, v92, v100
	v_add_f32_e32 v100, v93, v100
	v_cvt_pk_bf16_f32 v128, v88, v89
	v_cvt_pk_bf16_f32 v129, v90, v91
	ds_read_b64_tr_b16 v[88:89], v171 offset:29696
	ds_read_b64_tr_b16 v[90:91], v171 offset:30208
	s_waitcnt lgkmcnt(12)
	v_mfma_f32_32x32x16_bf16 v[32:47], v[108:111], v[132:135], v[32:47]
	v_add_f32_e32 v100, v94, v100
	v_add_f32_e32 v100, v95, v100
	v_add_f32_e32 v100, v64, v100
	v_add_f32_e32 v100, v65, v100
	v_cvt_pk_bf16_f32 v130, v92, v93
	v_cvt_pk_bf16_f32 v131, v94, v95
	ds_read_b64_tr_b16 v[92:93], v171 offset:26624
	ds_read_b64_tr_b16 v[94:95], v171 offset:27136
	s_waitcnt lgkmcnt(13)
	v_mfma_f32_32x32x16_bf16 v[48:63], v[144:147], v[124:127], v[48:63]
	v_add_f32_e32 v100, v66, v100
	v_add_f32_e32 v100, v67, v100
	v_add_f32_e32 v100, v68, v100
	v_add_f32_e32 v100, v69, v100
	v_cvt_pk_bf16_f32 v120, v64, v65
	v_cvt_pk_bf16_f32 v121, v66, v67
	ds_read_b64_tr_b16 v[180:181], v171 offset:30720
	ds_read_b64_tr_b16 v[182:183], v171 offset:31232
	s_waitcnt lgkmcnt(14)
	v_mfma_f32_32x32x16_bf16 v[32:47], v[148:151], v[124:127], v[32:47]
	v_add_f32_e32 v64, v70, v100
	v_add_f32_e32 v64, v71, v64
	v_add_f32_e32 v64, v72, v64
	v_add_f32_e32 v64, v73, v64
	v_cvt_pk_bf16_f32 v122, v68, v69
	v_cvt_pk_bf16_f32 v123, v70, v71
	ds_read_b64_tr_b16 v[184:185], v171 offset:27648
	ds_read_b64_tr_b16 v[186:187], v171 offset:28160
	s_waitcnt lgkmcnt(14)
	v_mfma_f32_32x32x16_bf16 v[48:63], v[172:175], v[116:119], v[48:63]
	v_add_f32_e32 v64, v74, v64
	v_add_f32_e32 v64, v75, v64
	v_add_f32_e32 v64, v76, v64
	v_add_f32_e32 v64, v77, v64
	v_cvt_pk_bf16_f32 v112, v72, v73
	v_cvt_pk_bf16_f32 v113, v74, v75
	ds_read_b64_tr_b16 v[72:73], v171 offset:31744
	ds_read_b64_tr_b16 v[74:75], v171 offset:32256
	v_mfma_f32_32x32x16_bf16 v[32:47], v[96:99], v[116:119], v[32:47]
	v_add_f32_e32 v64, v78, v64
	v_add_f32_e32 v64, v79, v64
	v_add_f32_e32 v171, 0, v64
	v_cvt_pk_bf16_f32 v114, v76, v77
	v_cvt_pk_bf16_f32 v115, v78, v79
	v_lshl_add_u64 v[64:65], v[158:159], 0, s[28:29]
	s_add_i32 s17, s57, s49
	s_mov_b32 s24, m0
	s_mov_b32 m0, s17
	s_nop 0
	global_load_lds_dwordx4 v[64:65], off
	s_mov_b32 m0, s24
	v_lshl_add_u64 v[156:157], v[156:157], 0, s[22:23]
	s_add_i32 s17, s16, s48
	s_mov_b32 s24, m0
	s_mov_b32 m0, s17
	s_nop 0
	global_load_lds_dwordx4 v[156:157], off
	s_mov_b32 m0, s24
	s_waitcnt lgkmcnt(14)
	v_mfma_f32_32x32x16_bf16 v[0:15], v[136:139], v[176:179], v[0:15]
	v_exp_f32_e32 v48, v48
	v_exp_f32_e32 v49, v49
	v_exp_f32_e32 v50, v50
	v_exp_f32_e32 v51, v51
	s_waitcnt lgkmcnt(12)
	v_mfma_f32_32x32x16_bf16 v[16:31], v[136:139], v[80:83], v[16:31]
	v_exp_f32_e32 v52, v52
	v_exp_f32_e32 v53, v53
	v_exp_f32_e32 v54, v54
	v_exp_f32_e32 v55, v55
	v_add_u32_e32 v76, s16, v165
	ds_read_b128 v[68:71], v76
	ds_read_b128 v[64:67], v76 offset:512
	s_waitcnt lgkmcnt(12)
	v_mfma_f32_32x32x16_bf16 v[0:15], v[128:131], v[84:87], v[0:15]
	v_exp_f32_e32 v56, v56
	v_exp_f32_e32 v57, v57
	v_exp_f32_e32 v58, v58
	v_exp_f32_e32 v59, v59
	ds_read_b128 v[148:151], v76 offset:2048
	ds_read_b128 v[144:147], v76 offset:2560
	s_waitcnt lgkmcnt(12)
	v_mfma_f32_32x32x16_bf16 v[16:31], v[128:131], v[88:91], v[16:31]
	v_exp_f32_e32 v60, v60
	v_exp_f32_e32 v61, v61
	v_exp_f32_e32 v62, v62
	v_exp_f32_e32 v63, v63
	ds_read_b128 v[108:111], v76 offset:4096
	ds_read_b128 v[104:107], v76 offset:4608
	s_waitcnt lgkmcnt(12)
	v_mfma_f32_32x32x16_bf16 v[0:15], v[120:123], v[92:95], v[0:15]
	v_exp_f32_e32 v32, v32
	v_exp_f32_e32 v33, v33
	v_exp_f32_e32 v34, v34
	v_exp_f32_e32 v35, v35
	ds_read_b128 v[100:103], v76 offset:6144
	ds_read_b128 v[96:99], v76 offset:6656
	s_waitcnt lgkmcnt(12)
	v_mfma_f32_32x32x16_bf16 v[16:31], v[120:123], v[180:183], v[16:31]
	v_exp_f32_e32 v36, v36
	v_exp_f32_e32 v37, v37
	v_exp_f32_e32 v38, v38
	v_exp_f32_e32 v39, v39
	s_waitcnt lgkmcnt(10)
	v_mfma_f32_32x32x16_bf16 v[0:15], v[112:115], v[184:187], v[0:15]
	v_exp_f32_e32 v40, v40
	v_exp_f32_e32 v41, v41
	v_exp_f32_e32 v42, v42
	v_exp_f32_e32 v43, v43
	s_waitcnt lgkmcnt(8)
	v_mfma_f32_32x32x16_bf16 v[16:31], v[112:115], v[72:75], v[16:31]
	v_exp_f32_e32 v44, v44
	v_exp_f32_e32 v45, v45
	v_exp_f32_e32 v46, v46
	v_exp_f32_e32 v47, v47
	s_add_i32 s17, s16, 0x2000
	s_waitcnt vmcnt(2) lgkmcnt(0)
	s_barrier
	s_cmpk_lg_i32 s16, 0x4000
	v_add_f32_e32 v72, v167, v170
	s_mov_b32 s59, s57
	s_cselect_b32 s57, s17, 0
	s_add_i32 s56, s56, 2
	v_lshl_add_u64 v[158:159], v[158:159], 0, s[22:23]
	s_mov_b32 s58, s16
	v_add_f32_e32 v167, v72, v171
	s_cmp_gt_u32 s56, 56
	s_cbranch_scc0 .LBB0_292
	s_and_b32 s17, s55, 0x3fffffc0
	s_cmp_lg_u32 0, -1
	s_cselect_b32 s16, 0, 0
	s_add_i32 s24, s16, 0x6000
	s_lshl_b32 s17, s17, 2
	v_add_u32_e32 v72, s24, v168
	s_add_i32 s24, s17, 0
	v_add3_u32 v156, v72, v166, v169
	ds_read_b64_tr_b16 v[168:169], v164 offset:32768
	ds_read_b64_tr_b16 v[170:171], v164 offset:33280
	v_add_f32_e32 v72, v48, v49
	v_add_f32_e32 v72, v50, v72
	v_add_f32_e32 v72, v51, v72
	v_add_f32_e32 v72, v52, v72
	v_add_f32_e32 v72, v53, v72
	v_cvt_pk_bf16_f32 v136, v48, v49
	v_cvt_pk_bf16_f32 v137, v50, v51
	s_waitcnt lgkmcnt(9)
	v_mfma_f32_32x32x16_bf16 v[80:95], v[68:71], v[140:143], 0
	ds_read_b64_tr_b16 v[48:49], v164 offset:36864
	ds_read_b64_tr_b16 v[50:51], v164 offset:37376
	v_add_f32_e32 v68, v54, v72
	v_add_f32_e32 v68, v55, v68
	v_add_f32_e32 v68, v56, v68
	v_add_f32_e32 v112, v57, v68
	v_cvt_pk_bf16_f32 v138, v52, v53
	v_cvt_pk_bf16_f32 v139, v54, v55
	s_waitcnt lgkmcnt(10)
	v_mfma_f32_32x32x16_bf16 v[64:79], v[64:67], v[140:143], 0
	ds_read_b64_tr_b16 v[52:53], v164 offset:33792
	ds_read_b64_tr_b16 v[54:55], v164 offset:34304
	v_add_f32_e32 v112, v58, v112
	v_add_f32_e32 v112, v59, v112
	v_add_f32_e32 v112, v60, v112
	v_add_f32_e32 v112, v61, v112
	v_cvt_pk_bf16_f32 v128, v56, v57
	v_cvt_pk_bf16_f32 v129, v58, v59
	s_waitcnt lgkmcnt(11)
	v_mfma_f32_32x32x16_bf16 v[80:95], v[148:151], v[132:135], v[80:95]
	ds_read_b64_tr_b16 v[56:57], v164 offset:37888
	ds_read_b64_tr_b16 v[58:59], v164 offset:38400
	v_add_f32_e32 v112, v62, v112
	v_add_f32_e32 v112, v63, v112
	v_add_f32_e32 v112, v32, v112
	v_add_f32_e32 v112, v33, v112
	v_cvt_pk_bf16_f32 v130, v60, v61
	v_cvt_pk_bf16_f32 v131, v62, v63
	s_waitcnt lgkmcnt(12)
	v_mfma_f32_32x32x16_bf16 v[64:79], v[144:147], v[132:135], v[64:79]
	ds_read_b64_tr_b16 v[60:61], v164 offset:34816
	ds_read_b64_tr_b16 v[62:63], v164 offset:35328
	s_waitcnt lgkmcnt(13)
	v_mfma_f32_32x32x16_bf16 v[80:95], v[108:111], v[124:127], v[80:95]
	v_add_f32_e32 v108, v34, v112
	v_add_f32_e32 v108, v35, v108
	v_add_f32_e32 v108, v36, v108
	v_add_f32_e32 v108, v37, v108
	v_cvt_pk_bf16_f32 v120, v32, v33
	v_cvt_pk_bf16_f32 v121, v34, v35
	ds_read_b64_tr_b16 v[32:33], v164 offset:38912
	ds_read_b64_tr_b16 v[34:35], v164 offset:39424
	s_waitcnt lgkmcnt(14)
	v_mfma_f32_32x32x16_bf16 v[64:79], v[104:107], v[124:127], v[64:79]
	v_add_f32_e32 v104, v38, v108
	v_add_f32_e32 v104, v39, v104
	v_add_f32_e32 v104, v40, v104
	v_add_f32_e32 v104, v41, v104
	v_cvt_pk_bf16_f32 v122, v36, v37
	v_cvt_pk_bf16_f32 v123, v38, v39
	ds_read_b64_tr_b16 v[36:37], v164 offset:35840
	ds_read_b64_tr_b16 v[38:39], v164 offset:36352
	s_waitcnt lgkmcnt(14)
	v_mfma_f32_32x32x16_bf16 v[80:95], v[100:103], v[116:119], v[80:95]
	v_add_f32_e32 v100, v42, v104
	v_add_f32_e32 v100, v43, v100
	v_add_f32_e32 v100, v44, v100
	v_add_f32_e32 v100, v45, v100
	v_cvt_pk_bf16_f32 v112, v40, v41
	v_cvt_pk_bf16_f32 v113, v42, v43
	ds_read_b64_tr_b16 v[40:41], v164 offset:39936
	ds_read_b64_tr_b16 v[42:43], v164 offset:40448
	v_mfma_f32_32x32x16_bf16 v[64:79], v[96:99], v[116:119], v[64:79]
	v_add_f32_e32 v96, v46, v100
	v_add_f32_e32 v96, v47, v96
	v_add_f32_e32 v96, 0, v96
	v_cvt_pk_bf16_f32 v114, v44, v45
	v_cvt_pk_bf16_f32 v115, v46, v47
	s_add_i32 s16, s16, s54
	v_lshl_add_u64 v[44:45], v[154:155], 0, s[66:67]
	s_add_i32 s17, s16, 0x4000
	s_mov_b32 s25, m0
	s_mov_b32 m0, s17
	s_nop 0
	global_load_lds_dwordx4 v[44:45], off
	s_mov_b32 m0, s25
	s_mov_b64 s[42:43], 0xf00000
	v_lshl_add_u64 v[44:45], v[152:153], 0, s[42:43]
	s_mov_b32 s17, m0
	s_mov_b32 m0, s48
	s_nop 0
	global_load_lds_dwordx4 v[44:45], off
	s_mov_b32 m0, s17
	v_add_f32_e32 v157, v167, v96
	s_waitcnt lgkmcnt(14)
	v_mfma_f32_32x32x16_bf16 v[0:15], v[136:139], v[168:171], v[0:15]
	v_exp_f32_e32 v80, v80
	v_exp_f32_e32 v81, v81
	v_exp_f32_e32 v82, v82
	v_exp_f32_e32 v83, v83
	s_waitcnt lgkmcnt(12)
	v_mfma_f32_32x32x16_bf16 v[16:31], v[136:139], v[48:51], v[16:31]
	v_exp_f32_e32 v84, v84
	v_exp_f32_e32 v85, v85
	v_exp_f32_e32 v86, v86
	v_exp_f32_e32 v87, v87
	ds_read_b128 v[44:47], v165
	ds_read_b128 v[144:147], v165 offset:512
	s_waitcnt lgkmcnt(12)
	v_mfma_f32_32x32x16_bf16 v[0:15], v[128:131], v[52:55], v[0:15]
	v_exp_f32_e32 v88, v88
	v_exp_f32_e32 v89, v89
	v_exp_f32_e32 v90, v90
	v_exp_f32_e32 v91, v91
	ds_read_b128 v[52:55], v165 offset:2048
	ds_read_b128 v[148:151], v165 offset:2560
	s_waitcnt lgkmcnt(12)
	v_mfma_f32_32x32x16_bf16 v[16:31], v[128:131], v[56:59], v[16:31]
	v_exp_f32_e32 v92, v92
	v_exp_f32_e32 v93, v93
	v_exp_f32_e32 v94, v94
	v_exp_f32_e32 v95, v95
	ds_read_b128 v[56:59], v165 offset:4096
	ds_read_b128 v[166:169], v165 offset:4608
	s_waitcnt lgkmcnt(12)
	v_mfma_f32_32x32x16_bf16 v[0:15], v[120:123], v[60:63], v[0:15]
	v_exp_f32_e32 v64, v64
	v_exp_f32_e32 v65, v65
	v_exp_f32_e32 v66, v66
	v_exp_f32_e32 v67, v67
	ds_read_b128 v[60:63], v165 offset:6144
	ds_read_b128 v[48:51], v165 offset:6656
	s_waitcnt lgkmcnt(12)
	v_mfma_f32_32x32x16_bf16 v[16:31], v[120:123], v[32:35], v[16:31]
	v_exp_f32_e32 v68, v68
	v_exp_f32_e32 v69, v69
	v_exp_f32_e32 v70, v70
	v_exp_f32_e32 v71, v71
	s_waitcnt lgkmcnt(10)
	v_mfma_f32_32x32x16_bf16 v[0:15], v[112:115], v[36:39], v[0:15]
	v_exp_f32_e32 v72, v72
	v_exp_f32_e32 v73, v73
	v_exp_f32_e32 v74, v74
	v_exp_f32_e32 v75, v75
	s_waitcnt lgkmcnt(8)
	v_mfma_f32_32x32x16_bf16 v[16:31], v[112:115], v[40:43], v[16:31]
	v_exp_f32_e32 v76, v76
	v_exp_f32_e32 v77, v77
	v_exp_f32_e32 v78, v78
	v_exp_f32_e32 v79, v79
	s_waitcnt vmcnt(2) lgkmcnt(0)
	s_barrier
	ds_read_b64_tr_b16 v[170:171], v164 offset:40960
	ds_read_b64_tr_b16 v[172:173], v164 offset:41472
	v_add_f32_e32 v32, v80, v81
	v_add_f32_e32 v32, v82, v32
	v_add_f32_e32 v32, v83, v32
	v_add_f32_e32 v32, v84, v32
	v_add_f32_e32 v32, v85, v32
	v_cvt_pk_bf16_f32 v136, v80, v81
	v_cvt_pk_bf16_f32 v137, v82, v83
	s_waitcnt lgkmcnt(9)
	v_mfma_f32_32x32x16_bf16 v[96:111], v[44:47], v[140:143], 0
	ds_read_b64_tr_b16 v[80:81], v164 offset:45056
	ds_read_b64_tr_b16 v[82:83], v164 offset:45568
	v_add_f32_e32 v32, v86, v32
	v_add_f32_e32 v32, v87, v32
	v_add_f32_e32 v32, v88, v32
	v_add_f32_e32 v112, v89, v32
	s_waitcnt lgkmcnt(10)
	v_mfma_f32_32x32x16_bf16 v[32:47], v[144:147], v[140:143], 0
	v_cvt_pk_bf16_f32 v138, v84, v85
	v_cvt_pk_bf16_f32 v139, v86, v87
	ds_read_b64_tr_b16 v[84:85], v164 offset:41984
	ds_read_b64_tr_b16 v[86:87], v164 offset:42496
	s_waitcnt lgkmcnt(11)
	v_mfma_f32_32x32x16_bf16 v[96:111], v[52:55], v[132:135], v[96:111]
	v_add_f32_e32 v52, v90, v112
	v_add_f32_e32 v52, v91, v52
	v_add_f32_e32 v52, v92, v52
	v_add_f32_e32 v112, v93, v52
	v_cvt_pk_bf16_f32 v128, v88, v89
	v_cvt_pk_bf16_f32 v129, v90, v91
	ds_read_b64_tr_b16 v[52:53], v164 offset:46080
	ds_read_b64_tr_b16 v[54:55], v164 offset:46592
	s_waitcnt lgkmcnt(12)
	v_mfma_f32_32x32x16_bf16 v[32:47], v[148:151], v[132:135], v[32:47]
	v_add_f32_e32 v88, v94, v112
	v_add_f32_e32 v88, v95, v88
	v_add_f32_e32 v88, v64, v88
	v_add_f32_e32 v112, v65, v88
	v_cvt_pk_bf16_f32 v130, v92, v93
	v_cvt_pk_bf16_f32 v131, v94, v95
	ds_read_b64_tr_b16 v[88:89], v164 offset:43008
	ds_read_b64_tr_b16 v[90:91], v164 offset:43520
	s_waitcnt lgkmcnt(13)
	v_mfma_f32_32x32x16_bf16 v[96:111], v[56:59], v[124:127], v[96:111]
	v_add_f32_e32 v56, v66, v112
	v_add_f32_e32 v56, v67, v56
	v_add_f32_e32 v56, v68, v56
	v_add_f32_e32 v92, v69, v56
	v_cvt_pk_bf16_f32 v120, v64, v65
	v_cvt_pk_bf16_f32 v121, v66, v67
	ds_read_b64_tr_b16 v[56:57], v164 offset:47104
	ds_read_b64_tr_b16 v[58:59], v164 offset:47616
	s_waitcnt lgkmcnt(14)
	v_mfma_f32_32x32x16_bf16 v[32:47], v[166:169], v[124:127], v[32:47]
	v_add_f32_e32 v64, v70, v92
	v_add_f32_e32 v64, v71, v64
	v_add_f32_e32 v64, v72, v64
	v_add_f32_e32 v92, v73, v64
	v_cvt_pk_bf16_f32 v122, v68, v69
	v_cvt_pk_bf16_f32 v123, v70, v71
	ds_read_b64_tr_b16 v[64:65], v164 offset:44032
	ds_read_b64_tr_b16 v[66:67], v164 offset:44544
	s_waitcnt lgkmcnt(14)
	v_mfma_f32_32x32x16_bf16 v[96:111], v[60:63], v[116:119], v[96:111]
	v_add_f32_e32 v60, v74, v92
	v_add_f32_e32 v60, v75, v60
	v_add_f32_e32 v60, v76, v60
	v_add_f32_e32 v68, v77, v60
	v_cvt_pk_bf16_f32 v112, v72, v73
	v_cvt_pk_bf16_f32 v113, v74, v75
	ds_read_b64_tr_b16 v[60:61], v164 offset:48128
	ds_read_b64_tr_b16 v[62:63], v164 offset:48640
	v_mfma_f32_32x32x16_bf16 v[32:47], v[48:51], v[116:119], v[32:47]
	v_add_f32_e32 v48, v78, v68
	v_add_f32_e32 v48, v79, v48
	v_add_f32_e32 v48, 0, v48
	v_cvt_pk_bf16_f32 v114, v76, v77
	v_cvt_pk_bf16_f32 v115, v78, v79
	s_mov_b64 s[42:43], 0xfc0000
	v_add_f32_e32 v157, v157, v48
	v_lshl_add_u64 v[48:49], v[154:155], 0, s[42:43]
	s_mov_b32 s17, m0
	s_mov_b32 m0, s49
	s_nop 0
	global_load_lds_dwordx4 v[48:49], off
	s_mov_b32 m0, s17
	s_mov_b64 s[54:55], 0xf40000
	v_lshl_add_u64 v[48:49], v[152:153], 0, s[54:55]
	s_add_i32 s17, s16, 0x8000
	s_mov_b32 s25, m0
	s_mov_b32 m0, s17
	s_nop 0
	global_load_lds_dwordx4 v[48:49], off
	s_mov_b32 m0, s25
	s_waitcnt lgkmcnt(14)
	v_mfma_f32_32x32x16_bf16 v[0:15], v[136:139], v[170:173], v[0:15]
	v_exp_f32_e32 v96, v96
	v_exp_f32_e32 v97, v97
	v_exp_f32_e32 v98, v98
	v_exp_f32_e32 v99, v99
	s_waitcnt lgkmcnt(12)
	v_mfma_f32_32x32x16_bf16 v[16:31], v[136:139], v[80:83], v[16:31]
	v_exp_f32_e32 v100, v100
	v_exp_f32_e32 v101, v101
	v_exp_f32_e32 v102, v102
	v_exp_f32_e32 v103, v103
	ds_read_b128 v[48:51], v165 offset:8192
	ds_read_b128 v[92:95], v165 offset:8704
	s_waitcnt lgkmcnt(12)
	v_mfma_f32_32x32x16_bf16 v[0:15], v[128:131], v[84:87], v[0:15]
	v_exp_f32_e32 v104, v104
	v_exp_f32_e32 v105, v105
	v_exp_f32_e32 v106, v106
	v_exp_f32_e32 v107, v107
	ds_read_b128 v[84:87], v165 offset:10240
	ds_read_b128 v[144:147], v165 offset:10752
	s_waitcnt lgkmcnt(12)
	v_mfma_f32_32x32x16_bf16 v[16:31], v[128:131], v[52:55], v[16:31]
	v_exp_f32_e32 v108, v108
	v_exp_f32_e32 v109, v109
	v_exp_f32_e32 v110, v110
	v_exp_f32_e32 v111, v111
	ds_read_b128 v[148:151], v165 offset:12288
	ds_read_b128 v[166:169], v165 offset:12800
	s_waitcnt lgkmcnt(12)
	v_mfma_f32_32x32x16_bf16 v[0:15], v[120:123], v[88:91], v[0:15]
	v_exp_f32_e32 v32, v32
	v_exp_f32_e32 v33, v33
	v_exp_f32_e32 v34, v34
	v_exp_f32_e32 v35, v35
	ds_read_b128 v[88:91], v165 offset:14336
	ds_read_b128 v[80:83], v165 offset:14848
	s_waitcnt lgkmcnt(12)
	v_mfma_f32_32x32x16_bf16 v[16:31], v[120:123], v[56:59], v[16:31]
	v_exp_f32_e32 v36, v36
	v_exp_f32_e32 v37, v37
	v_exp_f32_e32 v38, v38
	v_exp_f32_e32 v39, v39
	s_waitcnt lgkmcnt(10)
	v_mfma_f32_32x32x16_bf16 v[0:15], v[112:115], v[64:67], v[0:15]
	v_exp_f32_e32 v40, v40
	v_exp_f32_e32 v41, v41
	v_exp_f32_e32 v42, v42
	v_exp_f32_e32 v43, v43
	s_waitcnt lgkmcnt(8)
	v_mfma_f32_32x32x16_bf16 v[16:31], v[112:115], v[60:63], v[16:31]
	v_exp_f32_e32 v44, v44
	v_exp_f32_e32 v45, v45
	v_exp_f32_e32 v46, v46
	v_exp_f32_e32 v47, v47
	s_waitcnt vmcnt(2) lgkmcnt(0)
	s_barrier
	ds_read_b64_tr_b16 v[170:171], v164 offset:24576
	ds_read_b64_tr_b16 v[172:173], v164 offset:25088
	v_add_f32_e32 v52, v96, v97
	v_add_f32_e32 v52, v98, v52
	v_add_f32_e32 v52, v99, v52
	v_add_f32_e32 v52, v100, v52
	v_add_f32_e32 v52, v101, v52
	v_cvt_pk_bf16_f32 v136, v96, v97
	v_cvt_pk_bf16_f32 v137, v98, v99
	s_waitcnt lgkmcnt(9)
	v_mfma_f32_32x32x16_bf16 v[64:79], v[48:51], v[140:143], 0
	ds_read_b64_tr_b16 v[96:97], v164 offset:28672
	ds_read_b64_tr_b16 v[98:99], v164 offset:29184
	v_add_f32_e32 v48, v102, v52
	v_add_f32_e32 v48, v103, v48
	v_add_f32_e32 v48, v104, v48
	v_add_f32_e32 v112, v105, v48
	v_cvt_pk_bf16_f32 v138, v100, v101
	v_cvt_pk_bf16_f32 v139, v102, v103
	s_waitcnt lgkmcnt(10)
	v_mfma_f32_32x32x16_bf16 v[48:63], v[92:95], v[140:143], 0
	ds_read_b64_tr_b16 v[92:93], v164 offset:25600
	ds_read_b64_tr_b16 v[94:95], v164 offset:26112
	s_waitcnt lgkmcnt(11)
	v_mfma_f32_32x32x16_bf16 v[64:79], v[84:87], v[132:135], v[64:79]
	v_add_f32_e32 v84, v106, v112
	v_add_f32_e32 v84, v107, v84
	v_add_f32_e32 v84, v108, v84
	v_add_f32_e32 v100, v109, v84
	v_cvt_pk_bf16_f32 v128, v104, v105
	v_cvt_pk_bf16_f32 v129, v106, v107
	ds_read_b64_tr_b16 v[84:85], v164 offset:29696
	ds_read_b64_tr_b16 v[86:87], v164 offset:30208
	v_add_f32_e32 v100, v110, v100
	v_add_f32_e32 v100, v111, v100
	v_add_f32_e32 v100, v32, v100
	v_add_f32_e32 v104, v33, v100
	v_cvt_pk_bf16_f32 v130, v108, v109
	v_cvt_pk_bf16_f32 v131, v110, v111
	s_waitcnt lgkmcnt(12)
	v_mfma_f32_32x32x16_bf16 v[48:63], v[144:147], v[132:135], v[48:63]
	ds_read_b64_tr_b16 v[100:101], v164 offset:26624
	ds_read_b64_tr_b16 v[102:103], v164 offset:27136
	v_add_f32_e32 v104, v34, v104
	v_add_f32_e32 v104, v35, v104
	v_add_f32_e32 v104, v36, v104
	v_add_f32_e32 v104, v37, v104
	v_cvt_pk_bf16_f32 v120, v32, v33
	v_cvt_pk_bf16_f32 v121, v34, v35
	s_waitcnt lgkmcnt(13)
	v_mfma_f32_32x32x16_bf16 v[64:79], v[148:151], v[124:127], v[64:79]
	ds_read_b64_tr_b16 v[32:33], v164 offset:30720
	ds_read_b64_tr_b16 v[34:35], v164 offset:31232
	v_add_f32_e32 v104, v38, v104
	v_add_f32_e32 v104, v39, v104
	v_add_f32_e32 v104, v40, v104
	v_add_f32_e32 v104, v41, v104
	v_cvt_pk_bf16_f32 v122, v36, v37
	v_cvt_pk_bf16_f32 v123, v38, v39
	s_waitcnt lgkmcnt(14)
	v_mfma_f32_32x32x16_bf16 v[48:63], v[166:169], v[124:127], v[48:63]
	ds_read_b64_tr_b16 v[36:37], v164 offset:27648
	ds_read_b64_tr_b16 v[38:39], v164 offset:28160
	s_waitcnt lgkmcnt(14)
	v_mfma_f32_32x32x16_bf16 v[64:79], v[88:91], v[116:119], v[64:79]
	v_add_f32_e32 v88, v42, v104
	v_add_f32_e32 v88, v43, v88
	v_add_f32_e32 v88, v44, v88
	v_add_f32_e32 v88, v45, v88
	v_cvt_pk_bf16_f32 v112, v40, v41
	v_cvt_pk_bf16_f32 v113, v42, v43
	ds_read_b64_tr_b16 v[40:41], v164 offset:31744
	ds_read_b64_tr_b16 v[42:43], v164 offset:32256
	v_mfma_f32_32x32x16_bf16 v[48:63], v[80:83], v[116:119], v[48:63]
	v_add_f32_e32 v80, v46, v88
	v_add_f32_e32 v80, v47, v80
	v_add_f32_e32 v80, 0, v80
	v_cvt_pk_bf16_f32 v114, v44, v45
	v_cvt_pk_bf16_f32 v115, v46, v47
	v_lshl_add_u64 v[44:45], v[152:153], 0, s[66:67]
	s_add_i32 s16, s16, 0xa000
	s_mov_b32 s17, m0
	s_mov_b32 m0, s16
	s_nop 0
	global_load_lds_dwordx4 v[44:45], off
	s_mov_b32 m0, s17
	v_add_f32_e32 v154, v157, v80
	s_waitcnt lgkmcnt(14)
	v_mfma_f32_32x32x16_bf16 v[0:15], v[136:139], v[170:173], v[0:15]
	v_exp_f32_e32 v64, v64
	v_exp_f32_e32 v65, v65
	v_exp_f32_e32 v66, v66
	v_exp_f32_e32 v67, v67
	s_waitcnt lgkmcnt(12)
	v_mfma_f32_32x32x16_bf16 v[16:31], v[136:139], v[96:99], v[16:31]
	v_exp_f32_e32 v68, v68
	v_exp_f32_e32 v69, v69
	v_exp_f32_e32 v70, v70
	v_exp_f32_e32 v71, v71
	ds_read_b128 v[44:47], v165 offset:16384
	ds_read_b128 v[104:107], v165 offset:16896
	s_waitcnt lgkmcnt(12)
	v_mfma_f32_32x32x16_bf16 v[0:15], v[128:131], v[92:95], v[0:15]
	v_exp_f32_e32 v72, v72
	v_exp_f32_e32 v73, v73
	v_exp_f32_e32 v74, v74
	v_exp_f32_e32 v75, v75
	ds_read_b128 v[108:111], v165 offset:18432
	ds_read_b128 v[144:147], v165 offset:18944
	s_waitcnt lgkmcnt(12)
	v_mfma_f32_32x32x16_bf16 v[16:31], v[128:131], v[84:87], v[16:31]
	v_exp_f32_e32 v76, v76
	v_exp_f32_e32 v77, v77
	v_exp_f32_e32 v78, v78
	v_exp_f32_e32 v79, v79
	ds_read_b128 v[148:151], v165 offset:20480
	ds_read_b128 v[166:169], v165 offset:20992
	s_waitcnt lgkmcnt(12)
	v_mfma_f32_32x32x16_bf16 v[0:15], v[120:123], v[100:103], v[0:15]
	v_exp_f32_e32 v48, v48
	v_exp_f32_e32 v49, v49
	v_exp_f32_e32 v50, v50
	v_exp_f32_e32 v51, v51
	ds_read_b128 v[100:103], v165 offset:22528
	ds_read_b128 v[96:99], v165 offset:23040
	s_waitcnt lgkmcnt(12)
	v_mfma_f32_32x32x16_bf16 v[16:31], v[120:123], v[32:35], v[16:31]
	v_exp_f32_e32 v52, v52
	v_exp_f32_e32 v53, v53
	v_exp_f32_e32 v54, v54
	v_exp_f32_e32 v55, v55
	s_waitcnt lgkmcnt(10)
	v_mfma_f32_32x32x16_bf16 v[0:15], v[112:115], v[36:39], v[0:15]
	v_exp_f32_e32 v56, v56
	v_exp_f32_e32 v57, v57
	v_exp_f32_e32 v58, v58
	v_exp_f32_e32 v59, v59
	s_waitcnt lgkmcnt(8)
	v_mfma_f32_32x32x16_bf16 v[16:31], v[112:115], v[40:43], v[16:31]
	v_exp_f32_e32 v60, v60
	v_exp_f32_e32 v61, v61
	v_exp_f32_e32 v62, v62
	v_exp_f32_e32 v63, v63
	s_waitcnt vmcnt(1) lgkmcnt(0)
	s_barrier
	ds_read_b64_tr_b16 v[170:171], v164 offset:32768
	ds_read_b64_tr_b16 v[172:173], v164 offset:33280
	v_add_f32_e32 v32, v64, v65
	v_add_f32_e32 v32, v66, v32
	v_add_f32_e32 v32, v67, v32
	v_add_f32_e32 v32, v68, v32
	v_add_f32_e32 v32, v69, v32
	v_cvt_pk_bf16_f32 v136, v64, v65
	v_cvt_pk_bf16_f32 v137, v66, v67
	s_waitcnt lgkmcnt(9)
	v_mfma_f32_32x32x16_bf16 v[80:95], v[44:47], v[140:143], 0
	ds_read_b64_tr_b16 v[64:65], v164 offset:36864
	ds_read_b64_tr_b16 v[66:67], v164 offset:37376
	v_add_f32_e32 v32, v70, v32
	v_add_f32_e32 v32, v71, v32
	v_add_f32_e32 v32, v72, v32
	v_add_f32_e32 v112, v73, v32
	s_waitcnt lgkmcnt(10)
	v_mfma_f32_32x32x16_bf16 v[32:47], v[104:107], v[140:143], 0
	v_cvt_pk_bf16_f32 v138, v68, v69
	v_cvt_pk_bf16_f32 v139, v70, v71
	ds_read_b64_tr_b16 v[68:69], v164 offset:33792
	ds_read_b64_tr_b16 v[70:71], v164 offset:34304
	v_add_f32_e32 v104, v74, v112
	v_add_f32_e32 v104, v75, v104
	v_add_f32_e32 v104, v76, v104
	v_add_f32_e32 v104, v77, v104
	v_cvt_pk_bf16_f32 v128, v72, v73
	v_cvt_pk_bf16_f32 v129, v74, v75
	s_waitcnt lgkmcnt(11)
	v_mfma_f32_32x32x16_bf16 v[80:95], v[108:111], v[132:135], v[80:95]
	ds_read_b64_tr_b16 v[72:73], v164 offset:37888
	ds_read_b64_tr_b16 v[74:75], v164 offset:38400
	s_waitcnt lgkmcnt(12)
	v_mfma_f32_32x32x16_bf16 v[32:47], v[144:147], v[132:135], v[32:47]
	v_add_f32_e32 v104, v78, v104
	v_add_f32_e32 v104, v79, v104
	v_add_f32_e32 v104, v48, v104
	v_add_f32_e32 v104, v49, v104
	v_cvt_pk_bf16_f32 v130, v76, v77
	v_cvt_pk_bf16_f32 v131, v78, v79
	ds_read_b64_tr_b16 v[76:77], v164 offset:34816
	ds_read_b64_tr_b16 v[78:79], v164 offset:35328
	v_add_f32_e32 v104, v50, v104
	v_add_f32_e32 v104, v51, v104
	v_add_f32_e32 v104, v52, v104
	v_add_f32_e32 v104, v53, v104
	v_cvt_pk_bf16_f32 v120, v48, v49
	v_cvt_pk_bf16_f32 v121, v50, v51
	s_waitcnt lgkmcnt(13)
	v_mfma_f32_32x32x16_bf16 v[80:95], v[148:151], v[124:127], v[80:95]
	ds_read_b64_tr_b16 v[48:49], v164 offset:38912
	ds_read_b64_tr_b16 v[50:51], v164 offset:39424
	s_waitcnt lgkmcnt(14)
	v_mfma_f32_32x32x16_bf16 v[32:47], v[166:169], v[124:127], v[32:47]
	v_add_f32_e32 v104, v54, v104
	v_add_f32_e32 v104, v55, v104
	v_add_f32_e32 v104, v56, v104
	v_add_f32_e32 v104, v57, v104
	v_cvt_pk_bf16_f32 v122, v52, v53
	v_cvt_pk_bf16_f32 v123, v54, v55
	ds_read_b64_tr_b16 v[52:53], v164 offset:35840
	ds_read_b64_tr_b16 v[54:55], v164 offset:36352
	s_waitcnt lgkmcnt(14)
	v_mfma_f32_32x32x16_bf16 v[80:95], v[100:103], v[116:119], v[80:95]
	v_add_f32_e32 v100, v58, v104
	v_add_f32_e32 v100, v59, v100
	v_add_f32_e32 v100, v60, v100
	v_add_f32_e32 v100, v61, v100
	v_cvt_pk_bf16_f32 v112, v56, v57
	v_cvt_pk_bf16_f32 v113, v58, v59
	ds_read_b64_tr_b16 v[56:57], v164 offset:39936
	ds_read_b64_tr_b16 v[58:59], v164 offset:40448
	v_mfma_f32_32x32x16_bf16 v[32:47], v[96:99], v[116:119], v[32:47]
	v_add_f32_e32 v96, v62, v100
	v_add_f32_e32 v96, v63, v96
	v_add_f32_e32 v96, 0, v96
	v_cvt_pk_bf16_f32 v114, v60, v61
	v_cvt_pk_bf16_f32 v115, v62, v63
	v_lshl_add_u64 v[60:61], v[152:153], 0, s[42:43]
	s_mov_b32 s16, m0
	s_mov_b32 m0, s48
	s_nop 0
	global_load_lds_dwordx4 v[60:61], off
	s_mov_b32 m0, s16
	v_add_f32_e32 v100, v154, v96
	s_waitcnt lgkmcnt(14)
	v_mfma_f32_32x32x16_bf16 v[0:15], v[136:139], v[170:173], v[0:15]
	v_exp_f32_e32 v80, v80
	v_exp_f32_e32 v81, v81
	v_exp_f32_e32 v82, v82
	v_exp_f32_e32 v83, v83
	s_waitcnt lgkmcnt(12)
	v_mfma_f32_32x32x16_bf16 v[16:31], v[136:139], v[64:67], v[16:31]
	v_exp_f32_e32 v84, v84
	v_exp_f32_e32 v85, v85
	v_exp_f32_e32 v86, v86
	v_exp_f32_e32 v87, v87
	ds_read_b128 v[60:63], v165
	ds_read_b128 v[64:67], v165 offset:512
	s_waitcnt lgkmcnt(12)
	v_mfma_f32_32x32x16_bf16 v[0:15], v[128:131], v[68:71], v[0:15]
	v_exp_f32_e32 v88, v88
	v_exp_f32_e32 v89, v89
	v_exp_f32_e32 v90, v90
	v_exp_f32_e32 v91, v91
	ds_read_b128 v[102:105], v165 offset:2048
	ds_read_b128 v[106:109], v165 offset:2560
	s_waitcnt lgkmcnt(12)
	v_mfma_f32_32x32x16_bf16 v[16:31], v[128:131], v[72:75], v[16:31]
	v_exp_f32_e32 v92, v92
	v_exp_f32_e32 v93, v93
	v_exp_f32_e32 v94, v94
	v_exp_f32_e32 v95, v95
	ds_read_b128 v[144:147], v165 offset:4096
	ds_read_b128 v[148:151], v165 offset:4608
	s_waitcnt lgkmcnt(12)
	v_mfma_f32_32x32x16_bf16 v[0:15], v[120:123], v[76:79], v[0:15]
	v_exp_f32_e32 v32, v32
	v_exp_f32_e32 v33, v33
	v_exp_f32_e32 v34, v34
	v_exp_f32_e32 v35, v35
	ds_read_b128 v[152:155], v165 offset:6144
	ds_read_b128 v[96:99], v165 offset:6656
	s_waitcnt lgkmcnt(12)
	v_mfma_f32_32x32x16_bf16 v[16:31], v[120:123], v[48:51], v[16:31]
	v_exp_f32_e32 v36, v36
	v_exp_f32_e32 v37, v37
	v_exp_f32_e32 v38, v38
	v_exp_f32_e32 v39, v39
	s_waitcnt lgkmcnt(10)
	v_mfma_f32_32x32x16_bf16 v[0:15], v[112:115], v[52:55], v[0:15]
	v_exp_f32_e32 v40, v40
	v_exp_f32_e32 v41, v41
	v_exp_f32_e32 v42, v42
	v_exp_f32_e32 v43, v43
	s_waitcnt lgkmcnt(8)
	v_mfma_f32_32x32x16_bf16 v[16:31], v[112:115], v[56:59], v[16:31]
	v_exp_f32_e32 v44, v44
	v_exp_f32_e32 v45, v45
	v_exp_f32_e32 v46, v46
	v_exp_f32_e32 v47, v47
	s_waitcnt vmcnt(0) lgkmcnt(0)
	s_barrier
	s_mov_b32 s78, 0
	s_cmp_lg_u32 s3, 0x100
	s_cbranch_scc1 .Lgqa_nopf
	s_add_i32 s79, s19, s3
	s_cmpk_gt_i32 s79, 0x9ff
	s_cbranch_scc1 .Lgqa_nopf
	s_add_u32 s80, s76, 0x2000000
	s_addc_u32 s81, s77, 0
	v_lshlrev_b32_e32 v212, 12, v162
	v_lshl_or_b32 v212, v163, 4, v212
	global_load_dwordx4 v[196:199], v212, s[80:81] offset:1536
	global_load_dwordx4 v[200:203], v212, s[80:81] offset:1568
	global_load_dwordx4 v[204:207], v212, s[80:81] offset:1600
	global_load_dwordx4 v[208:211], v212, s[80:81] offset:1632
	s_mov_b64 s[80:81], 0x2000a00
	v_lshl_add_u64 v[212:213], v[194:195], 0, s[80:81]
	s_mov_b32 s80, s49
	s_mov_b32 s79, m0
	s_mov_b32 m0, s80
	s_nop 0
	global_load_lds_dwordx4 v[212:213], off
	s_mov_b32 m0, s79
	s_mov_b64 s[80:81], 0x2040a00
	v_lshl_add_u64 v[212:213], v[194:195], 0, s[80:81]
	s_add_i32 s80, s49, 0x2000
	s_mov_b32 s79, m0
	s_mov_b32 m0, s80
	s_nop 0
	global_load_lds_dwordx4 v[212:213], off
	s_mov_b32 m0, s79
	s_mov_b64 s[80:81], 0x2080a00
	v_lshl_add_u64 v[212:213], v[194:195], 0, s[80:81]
	s_add_i32 s80, s49, 0x4000
	s_mov_b32 s79, m0
	s_mov_b32 m0, s80
	s_nop 0
	global_load_lds_dwordx4 v[212:213], off
	s_mov_b32 m0, s79
	s_mov_b32 s78, 1
